# GDN scan chunk loop rewritten: qa/ma operands via LDS-DMA with swizzled source shared by the two column-half waves, outputs transposed through LDS into 16-byte row stores
# speedup vs baseline: 1.0520x; 1.0520x over previous
.LBB0_791:
	s_ashr_i32 s41, s40, 31
	v_mov_b64_e32 v[2:3], s[40:41]
	v_mad_u64_u32 v[2:3], s[0:1], v170, s84, v[2:3]
	v_mov_b32_e32 v0, v3
	s_movk_i32 s22, 0x80
	v_mad_u64_u32 v[4:5], s[0:1], v171, s84, v[0:1]
	v_cmp_gt_u32_e64 s[38:39], s22, v169
	v_mov_b32_e32 v3, v4
	s_lshl_b32 s12, s13, 6
	v_cndmask_b32_e64 v0, v196, v197, s[38:39]
	v_lshlrev_b64 v[2:3], 3, v[2:3]
	v_or3_b32 v4, v199, s12, v201
	v_lshl_add_u64 v[6:7], s[92:93], 0, v[0:1]
	v_mov_b32_e32 v5, v1
	v_lshl_add_u64 v[14:15], v[4:5], 1, v[6:7]
	v_or_b32_e32 v6, s13, v2
	v_lshlrev_b32_e32 v0, 7, v199
	v_mad_u64_u32 v[4:5], s[42:43], s51, v6, v[0:1]
	v_mul_lo_u32 v7, s51, v3
	v_and_b32_e32 v0, 32, v169
	v_and_b32_e32 v8, 63, v169
	v_add_u32_e32 v5, v7, v5
	v_lshrrev_b32_e32 v0, 1, v0
	v_lshl_add_u64 v[2:3], v[4:5], 0, v[0:1]
	v_lshlrev_b32_e32 v0, 5, v8
	v_lshl_add_u64 v[172:173], s[92:93], 0, v[2:3]
	v_lshl_or_b32 v2, v48, 11, v0
	v_or_b32_e32 v0, 0x1000, v2
	v_mov_b32_e32 v3, v1
	v_mad_u64_u32 v[4:5], s[42:43], s51, v6, v[0:1]
	v_mad_u64_u32 v[2:3], s[42:43], s51, v6, v[2:3]
	v_lshlrev_b32_e32 v202, 2, v200
	v_add_u32_e32 v5, v7, v5
	v_add_u32_e32 v3, v7, v3
	s_mul_hi_i32 s1, s40, s85
	s_mul_i32 s0, s40, s85
	s_mov_b32 s22, 0
	v_or_b32_e32 v203, 1, v202
	v_or_b32_e32 v204, 2, v202
	v_or_b32_e32 v205, 3, v202
	v_or_b32_e32 v206, 8, v202
	v_or_b32_e32 v207, 9, v202
	v_or_b32_e32 v208, 10, v202
	v_or_b32_e32 v209, 11, v202
	v_or_b32_e32 v210, 16, v202
	v_or_b32_e32 v211, 17, v202
	v_or_b32_e32 v212, 18, v202
	v_or_b32_e32 v213, 19, v202
	v_or_b32_e32 v214, 24, v202
	v_or_b32_e32 v215, 25, v202
	v_or_b32_e32 v216, 26, v202
	v_or_b32_e32 v217, 27, v202
	v_or_b32_e32 v218, 32, v202
	v_or_b32_e32 v219, 33, v202
	v_or_b32_e32 v220, 34, v202
	v_or_b32_e32 v221, 35, v202
	v_or_b32_e32 v222, 40, v202
	v_or_b32_e32 v223, 41, v202
	v_or_b32_e32 v224, 42, v202
	v_or_b32_e32 v225, 43, v202
	v_or_b32_e32 v226, 48, v202
	v_or_b32_e32 v227, 49, v202
	v_or_b32_e32 v228, 50, v202
	v_or_b32_e32 v229, 51, v202
	v_or_b32_e32 v230, 56, v202
	v_or_b32_e32 v231, 57, v202
	v_or_b32_e32 v232, 58, v202
	v_or_b32_e32 v233, 59, v202
	v_lshl_add_u64 v[174:175], s[92:93], 0, v[4:5]
	v_lshl_add_u64 v[176:177], s[92:93], 0, v[2:3]
	s_mov_b64 s[42:43], 0
	v_readlane_b32 s23, v248, 26
	s_mov_b64 s[22:23], 0x8000
	s_lshr_b32 s42, s48, 16
	v_readlane_b32 s43, v248, 26
	s_lshl_b32 s43, s43, 6
	s_add_i32 s43, s43, 63
	s_cmp_lg_u64 s[38:39], 0
	s_movk_i32 s14, 0x4000
	s_mov_b32 s15, 0
	s_cbranch_scc1 .Lscan_fwd
	s_mov_b32 s14, 0xffffc000
	s_mov_b32 s15, -1
.Lscan_fwd:
	v_and_b32_e32 v0, 63, v169
	v_lshrrev_b32_e32 v246, 6, v169
	v_lshlrev_b32_e32 v247, 13, v246
	s_nop 1
	v_readfirstlane_b32 s16, v247
	v_lshlrev_b32_e32 v246, 11, v246
	v_add_u32_e32 v246, 0x10000, v246
	v_lshl_add_u32 v237, v0, 4, v246
	v_lshl_add_u32 v236, v200, 8, v246
	v_lshl_add_u32 v236, v199, 1, v236
	v_and_b32_e32 v246, 0x4000, v247
	v_lshl_add_u32 v246, v199, 7, v246
	v_and_b32_e32 v247, 7, v199
	v_mov_b32_e32 v6, v200
	v_xor_b32_e32 v6, v6, v247
	v_lshl_add_u32 v6, v6, 4, v246
	v_or_b32_e32 v7, 2, v200
	v_xor_b32_e32 v7, v7, v247
	v_lshl_add_u32 v7, v7, 4, v246
	v_or_b32_e32 v8, 4, v200
	v_xor_b32_e32 v8, v8, v247
	v_lshl_add_u32 v8, v8, 4, v246
	v_or_b32_e32 v9, 6, v200
	v_xor_b32_e32 v9, v9, v247
	v_lshl_add_u32 v9, v9, 4, v246
	v_lshrrev_b32_e32 v247, 2, v0
	v_and_b32_e32 v246, 3, v0
	v_sub_u32_e32 v244, s43, v247
	v_cndmask_b32_e64 v244, v244, v247, s[38:39]
	v_mov_b32_e32 v245, 0
	v_lshl_add_u64 v[244:245], s[0:1], 0, v[244:245]
	v_lshlrev_b64 v[244:245], 10, v[244:245]
	v_lshl_add_u64 v[244:245], v[244:245], 0, v[14:15]
	v_lshlrev_b32_e32 v246, 4, v246
	v_lshlrev_b32_e32 v247, 1, v199
	v_sub_u32_e32 v246, v246, v247
	v_ashrrev_i32_e32 v247, 31, v246
	v_lshl_add_u64 v[244:245], v[244:245], 0, v[246:247]
	v_lshrrev_b32_e32 v246, 3, v0
	v_and_b32_e32 v247, 7, v0
	v_xor_b32_e32 v247, v247, v246
	v_lshlrev_b32_e32 v247, 4, v247
	v_lshl_add_u32 v247, v246, 7, v247
	v_lshlrev_b32_e32 v246, 7, v199
	v_lshl_add_u32 v246, v200, 4, v246
	v_sub_u32_e32 v246, v247, v246
	v_lshrrev_b32_e32 v247, 6, v169
	v_and_b32_e32 v247, 1, v247
	v_lshl_add_u32 v246, v247, 13, v246
	v_ashrrev_i32_e32 v247, 31, v246
	v_lshl_add_u64 v[246:247], v[172:173], 0, v[246:247]
	v_add_co_u32_e32 v2, vcc, 0x9b0e000, v246
	s_nop 1
	v_addc_co_u32_e32 v3, vcc, 0, v247, vcc
	v_add_co_u32_e32 v4, vcc, 0x9b0f000, v246
	s_nop 1
	v_addc_co_u32_e32 v5, vcc, 0, v247, vcc
	v_add_co_u32_e32 v10, vcc, 0x9b12000, v176
	s_nop 1
	v_addc_co_u32_e32 v11, vcc, 0, v177, vcc
	v_add_co_u32_e32 v12, vcc, 0x9b14000, v176
	s_nop 1
	v_addc_co_u32_e32 v13, vcc, 0, v177, vcc
	v_add_co_u32_e32 v160, vcc, 0x9b12000, v174
	s_nop 1
	v_addc_co_u32_e32 v161, vcc, 0, v175, vcc
	v_add_co_u32_e32 v162, vcc, 0x9b14000, v174
	s_nop 1
	v_addc_co_u32_e32 v163, vcc, 0, v175, vcc
	global_load_dwordx4 v[56:59], v[10:11], off
	global_load_dwordx4 v[60:63], v[10:11], off offset:16
	global_load_dwordx4 v[72:75], v[160:161], off
	global_load_dwordx4 v[76:79], v[160:161], off offset:16
	v_lshl_add_u64 v[10:11], v[10:11], 0, s[22:23]
	v_lshl_add_u64 v[160:161], v[160:161], 0, s[22:23]
	s_add_u32 m0, s16, 0x0
	s_nop 0
	global_load_lds_dwordx4 v[2:3], off
	global_load_lds_dwordx4 v[2:3], off offset:1024
	global_load_lds_dwordx4 v[2:3], off offset:2048
	global_load_lds_dwordx4 v[2:3], off offset:3072
	s_add_u32 m0, s16, 0x1000
	s_nop 0
	global_load_lds_dwordx4 v[4:5], off
	global_load_lds_dwordx4 v[4:5], off offset:1024
	global_load_lds_dwordx4 v[4:5], off offset:2048
	global_load_lds_dwordx4 v[4:5], off offset:3072
	v_lshl_add_u64 v[2:3], v[2:3], 0, s[22:23]
	v_lshl_add_u64 v[4:5], v[4:5], 0, s[22:23]
	global_load_dwordx4 v[88:91], v[12:13], off
	global_load_dwordx4 v[92:95], v[12:13], off offset:16
	v_lshl_add_u64 v[12:13], v[12:13], 0, s[22:23]
	global_load_dwordx4 v[104:107], v[162:163], off
	global_load_dwordx4 v[108:111], v[162:163], off offset:16
	v_lshl_add_u64 v[162:163], v[162:163], 0, s[22:23]
	s_waitcnt vmcnt(0)
.Lscan_loop:
	v_cvt_pk_bf16_f32 v112, v16, v17
	v_cvt_pk_bf16_f32 v113, v18, v19
	v_cvt_pk_bf16_f32 v114, v20, v21
	v_cvt_pk_bf16_f32 v115, v22, v23
	v_cvt_pk_bf16_f32 v116, v24, v25
	v_cvt_pk_bf16_f32 v117, v26, v27
	v_cvt_pk_bf16_f32 v118, v28, v29
	v_cvt_pk_bf16_f32 v119, v30, v31
	v_cvt_pk_bf16_f32 v120, v32, v33
	v_cvt_pk_bf16_f32 v121, v34, v35
	v_cvt_pk_bf16_f32 v122, v36, v37
	v_cvt_pk_bf16_f32 v123, v38, v39
	v_cvt_pk_bf16_f32 v124, v40, v41
	v_cvt_pk_bf16_f32 v125, v42, v43
	v_cvt_pk_bf16_f32 v126, v44, v45
	v_cvt_pk_bf16_f32 v127, v46, v47
	global_load_dwordx4 v[24:27], v[10:11], off
	global_load_dwordx4 v[28:31], v[10:11], off offset:16
	global_load_dwordx4 v[40:43], v[160:161], off
	global_load_dwordx4 v[44:47], v[160:161], off offset:16
	v_lshl_add_u64 v[10:11], v[10:11], 0, s[22:23]
	v_lshl_add_u64 v[160:161], v[160:161], 0, s[22:23]
	s_waitcnt vmcnt(12)
	s_barrier
	s_add_u32 m0, s16, 0x8000
	s_nop 0
	global_load_lds_dwordx4 v[2:3], off
	global_load_lds_dwordx4 v[2:3], off offset:1024
	global_load_lds_dwordx4 v[2:3], off offset:2048
	global_load_lds_dwordx4 v[2:3], off offset:3072
	s_add_u32 m0, s16, 0x9000
	s_nop 0
	global_load_lds_dwordx4 v[4:5], off
	global_load_lds_dwordx4 v[4:5], off offset:1024
	global_load_lds_dwordx4 v[4:5], off offset:2048
	global_load_lds_dwordx4 v[4:5], off offset:3072
	v_lshl_add_u64 v[2:3], v[2:3], 0, s[22:23]
	v_lshl_add_u64 v[4:5], v[4:5], 0, s[22:23]
	ds_read_b128 v[128:131], v6 offset:0
	ds_read_b128 v[132:135], v7 offset:0
	ds_read_b128 v[136:139], v8 offset:0
	ds_read_b128 v[140:143], v9 offset:0
	ds_read_b128 v[144:147], v6 offset:4096
	ds_read_b128 v[148:151], v7 offset:4096
	ds_read_b128 v[152:155], v8 offset:4096
	ds_read_b128 v[156:159], v9 offset:4096
	ds_read_b128 v[204:207], v6 offset:8192
	ds_read_b128 v[208:211], v7 offset:8192
	ds_read_b128 v[212:215], v8 offset:8192
	ds_read_b128 v[216:219], v9 offset:8192
	ds_read_b128 v[220:223], v6 offset:12288
	ds_read_b128 v[224:227], v7 offset:12288
	ds_read_b128 v[228:231], v8 offset:12288
	ds_read_b128 v[232:235], v9 offset:12288
	s_waitcnt vmcnt(16)
	v_lshlrev_b32_e32 v48, 16, v56
	v_and_b32_e32 v49, 0xffff0000, v56
	v_lshlrev_b32_e32 v50, 16, v57
	v_and_b32_e32 v51, 0xffff0000, v57
	v_lshlrev_b32_e32 v52, 16, v58
	v_and_b32_e32 v53, 0xffff0000, v58
	v_lshlrev_b32_e32 v54, 16, v59
	v_and_b32_e32 v55, 0xffff0000, v59
	v_lshlrev_b32_e32 v56, 16, v60
	v_and_b32_e32 v57, 0xffff0000, v60
	v_lshlrev_b32_e32 v58, 16, v61
	v_and_b32_e32 v59, 0xffff0000, v61
	v_lshlrev_b32_e32 v60, 16, v62
	v_and_b32_e32 v61, 0xffff0000, v62
	v_lshlrev_b32_e32 v62, 16, v63
	v_and_b32_e32 v63, 0xffff0000, v63
	v_lshlrev_b32_e32 v80, 16, v88
	v_and_b32_e32 v81, 0xffff0000, v88
	v_lshlrev_b32_e32 v82, 16, v89
	v_and_b32_e32 v83, 0xffff0000, v89
	v_lshlrev_b32_e32 v84, 16, v90
	v_and_b32_e32 v85, 0xffff0000, v90
	v_lshlrev_b32_e32 v86, 16, v91
	v_and_b32_e32 v87, 0xffff0000, v91
	v_lshlrev_b32_e32 v88, 16, v92
	v_and_b32_e32 v89, 0xffff0000, v92
	v_lshlrev_b32_e32 v90, 16, v93
	v_and_b32_e32 v91, 0xffff0000, v93
	v_lshlrev_b32_e32 v92, 16, v94
	v_and_b32_e32 v93, 0xffff0000, v94
	v_lshlrev_b32_e32 v94, 16, v95
	v_and_b32_e32 v95, 0xffff0000, v95
	v_lshlrev_b32_e32 v64, 16, v72
	v_and_b32_e32 v65, 0xffff0000, v72
	v_lshlrev_b32_e32 v66, 16, v73
	v_and_b32_e32 v67, 0xffff0000, v73
	v_lshlrev_b32_e32 v68, 16, v74
	v_and_b32_e32 v69, 0xffff0000, v74
	v_lshlrev_b32_e32 v70, 16, v75
	v_and_b32_e32 v71, 0xffff0000, v75
	v_lshlrev_b32_e32 v72, 16, v76
	v_and_b32_e32 v73, 0xffff0000, v76
	v_lshlrev_b32_e32 v74, 16, v77
	v_and_b32_e32 v75, 0xffff0000, v77
	v_lshlrev_b32_e32 v76, 16, v78
	v_and_b32_e32 v77, 0xffff0000, v78
	v_lshlrev_b32_e32 v78, 16, v79
	v_and_b32_e32 v79, 0xffff0000, v79
	v_lshlrev_b32_e32 v96, 16, v104
	v_and_b32_e32 v97, 0xffff0000, v104
	v_lshlrev_b32_e32 v98, 16, v105
	v_and_b32_e32 v99, 0xffff0000, v105
	v_lshlrev_b32_e32 v100, 16, v106
	v_and_b32_e32 v101, 0xffff0000, v106
	v_lshlrev_b32_e32 v102, 16, v107
	v_and_b32_e32 v103, 0xffff0000, v107
	v_lshlrev_b32_e32 v104, 16, v108
	v_and_b32_e32 v105, 0xffff0000, v108
	v_lshlrev_b32_e32 v106, 16, v109
	v_and_b32_e32 v107, 0xffff0000, v109
	v_lshlrev_b32_e32 v108, 16, v110
	v_and_b32_e32 v109, 0xffff0000, v110
	v_lshlrev_b32_e32 v110, 16, v111
	v_and_b32_e32 v111, 0xffff0000, v111
	s_waitcnt lgkmcnt(0)
	v_mfma_f32_32x32x16_bf16 v[48:63], v[204:207], v[112:115], v[48:63]
	v_mfma_f32_32x32x16_bf16 v[80:95], v[128:131], v[112:115], v[80:95]
	v_mfma_f32_32x32x16_bf16 v[64:79], v[220:223], v[112:115], v[64:79]
	v_mfma_f32_32x32x16_bf16 v[96:111], v[144:147], v[112:115], v[96:111]
	v_mfma_f32_32x32x16_bf16 v[48:63], v[208:211], v[116:119], v[48:63]
	v_mfma_f32_32x32x16_bf16 v[80:95], v[132:135], v[116:119], v[80:95]
	v_mfma_f32_32x32x16_bf16 v[64:79], v[224:227], v[116:119], v[64:79]
	v_mfma_f32_32x32x16_bf16 v[96:111], v[148:151], v[116:119], v[96:111]
	v_mfma_f32_32x32x16_bf16 v[48:63], v[212:215], v[120:123], v[48:63]
	v_mfma_f32_32x32x16_bf16 v[80:95], v[136:139], v[120:123], v[80:95]
	v_mfma_f32_32x32x16_bf16 v[64:79], v[228:231], v[120:123], v[64:79]
	v_mfma_f32_32x32x16_bf16 v[96:111], v[152:155], v[120:123], v[96:111]
	v_mfma_f32_32x32x16_bf16 v[48:63], v[216:219], v[124:127], v[48:63]
	v_mfma_f32_32x32x16_bf16 v[80:95], v[140:143], v[124:127], v[80:95]
	v_mfma_f32_32x32x16_bf16 v[64:79], v[232:235], v[124:127], v[64:79]
	v_mfma_f32_32x32x16_bf16 v[96:111], v[156:159], v[124:127], v[96:111]
	s_nop 9
	v_cvt_pk_bf16_f32 v112, v80, v81
	v_cvt_pk_bf16_f32 v113, v82, v83
	v_cvt_pk_bf16_f32 v114, v84, v85
	v_cvt_pk_bf16_f32 v115, v86, v87
	v_cvt_pk_bf16_f32 v116, v88, v89
	v_cvt_pk_bf16_f32 v117, v90, v91
	v_cvt_pk_bf16_f32 v118, v92, v93
	v_cvt_pk_bf16_f32 v119, v94, v95
	v_cvt_pk_bf16_f32 v120, v96, v97
	v_cvt_pk_bf16_f32 v121, v98, v99
	v_cvt_pk_bf16_f32 v122, v100, v101
	v_cvt_pk_bf16_f32 v123, v102, v103
	v_cvt_pk_bf16_f32 v124, v104, v105
	v_cvt_pk_bf16_f32 v125, v106, v107
	v_cvt_pk_bf16_f32 v126, v108, v109
	v_cvt_pk_bf16_f32 v127, v110, v111
	global_load_dwordx4 v[88:91], v[12:13], off
	global_load_dwordx4 v[92:95], v[12:13], off offset:16
	v_lshl_add_u64 v[12:13], v[12:13], 0, s[22:23]
	global_load_dwordx4 v[104:107], v[162:163], off
	global_load_dwordx4 v[108:111], v[162:163], off offset:16
	v_lshl_add_u64 v[162:163], v[162:163], 0, s[22:23]
	ds_write_b16 v236, v112 offset:0
	ds_write_b16_d16_hi v236, v112 offset:64
	ds_write_b16 v236, v113 offset:128
	ds_write_b16_d16_hi v236, v113 offset:192
	ds_write_b16 v236, v114 offset:512
	ds_write_b16_d16_hi v236, v114 offset:576
	ds_write_b16 v236, v115 offset:640
	ds_write_b16_d16_hi v236, v115 offset:704
	ds_write_b16 v236, v116 offset:1024
	ds_write_b16_d16_hi v236, v116 offset:1088
	ds_write_b16 v236, v117 offset:1152
	ds_write_b16_d16_hi v236, v117 offset:1216
	ds_write_b16 v236, v118 offset:1536
	ds_write_b16_d16_hi v236, v118 offset:1600
	ds_write_b16 v236, v119 offset:1664
	ds_write_b16_d16_hi v236, v119 offset:1728
	s_waitcnt lgkmcnt(0)
	ds_read_b128 v[80:83], v237 offset:0
	ds_read_b128 v[84:87], v237 offset:1024
	s_waitcnt lgkmcnt(0)
	global_store_dwordx4 v[244:245], v[80:83], off
	v_lshl_add_u64 v[244:245], v[244:245], 0, s[14:15]
	global_store_dwordx4 v[244:245], v[84:87], off
	v_lshl_add_u64 v[244:245], v[244:245], 0, s[14:15]
	ds_write_b16 v236, v120 offset:0
	ds_write_b16_d16_hi v236, v120 offset:64
	ds_write_b16 v236, v121 offset:128
	ds_write_b16_d16_hi v236, v121 offset:192
	ds_write_b16 v236, v122 offset:512
	ds_write_b16_d16_hi v236, v122 offset:576
	ds_write_b16 v236, v123 offset:640
	ds_write_b16_d16_hi v236, v123 offset:704
	ds_write_b16 v236, v124 offset:1024
	ds_write_b16_d16_hi v236, v124 offset:1088
	ds_write_b16 v236, v125 offset:1152
	ds_write_b16_d16_hi v236, v125 offset:1216
	ds_write_b16 v236, v126 offset:1536
	ds_write_b16_d16_hi v236, v126 offset:1600
	ds_write_b16 v236, v127 offset:1664
	ds_write_b16_d16_hi v236, v127 offset:1728
	s_waitcnt lgkmcnt(0)
	ds_read_b128 v[96:99], v237 offset:0
	ds_read_b128 v[100:103], v237 offset:1024
	s_waitcnt lgkmcnt(0)
	global_store_dwordx4 v[244:245], v[96:99], off
	v_lshl_add_u64 v[244:245], v[244:245], 0, s[14:15]
	global_store_dwordx4 v[244:245], v[100:103], off
	v_lshl_add_u64 v[244:245], v[244:245], 0, s[14:15]
	v_cvt_pk_bf16_f32 v112, v48, v49
	v_cvt_pk_bf16_f32 v113, v50, v51
	v_cvt_pk_bf16_f32 v114, v52, v53
	v_cvt_pk_bf16_f32 v115, v54, v55
	v_cvt_pk_bf16_f32 v116, v56, v57
	v_cvt_pk_bf16_f32 v117, v58, v59
	v_cvt_pk_bf16_f32 v118, v60, v61
	v_cvt_pk_bf16_f32 v119, v62, v63
	v_cvt_pk_bf16_f32 v120, v64, v65
	v_cvt_pk_bf16_f32 v121, v66, v67
	v_cvt_pk_bf16_f32 v122, v68, v69
	v_cvt_pk_bf16_f32 v123, v70, v71
	v_cvt_pk_bf16_f32 v124, v72, v73
	v_cvt_pk_bf16_f32 v125, v74, v75
	v_cvt_pk_bf16_f32 v126, v76, v77
	v_cvt_pk_bf16_f32 v127, v78, v79
	global_load_dwordx4 v[56:59], v[10:11], off
	global_load_dwordx4 v[60:63], v[10:11], off offset:16
	global_load_dwordx4 v[72:75], v[160:161], off
	global_load_dwordx4 v[76:79], v[160:161], off offset:16
	v_lshl_add_u64 v[10:11], v[10:11], 0, s[22:23]
	v_lshl_add_u64 v[160:161], v[160:161], 0, s[22:23]
	s_waitcnt vmcnt(12)
	s_barrier
	s_add_u32 m0, s16, 0x0
	s_nop 0
	global_load_lds_dwordx4 v[2:3], off
	global_load_lds_dwordx4 v[2:3], off offset:1024
	global_load_lds_dwordx4 v[2:3], off offset:2048
	global_load_lds_dwordx4 v[2:3], off offset:3072
	s_add_u32 m0, s16, 0x1000
	s_nop 0
	global_load_lds_dwordx4 v[4:5], off
	global_load_lds_dwordx4 v[4:5], off offset:1024
	global_load_lds_dwordx4 v[4:5], off offset:2048
	global_load_lds_dwordx4 v[4:5], off offset:3072
	v_lshl_add_u64 v[2:3], v[2:3], 0, s[22:23]
	v_lshl_add_u64 v[4:5], v[4:5], 0, s[22:23]
	ds_read_b128 v[128:131], v6 offset:32768
	ds_read_b128 v[132:135], v7 offset:32768
	ds_read_b128 v[136:139], v8 offset:32768
	ds_read_b128 v[140:143], v9 offset:32768
	ds_read_b128 v[144:147], v6 offset:36864
	ds_read_b128 v[148:151], v7 offset:36864
	ds_read_b128 v[152:155], v8 offset:36864
	ds_read_b128 v[156:159], v9 offset:36864
	ds_read_b128 v[204:207], v6 offset:40960
	ds_read_b128 v[208:211], v7 offset:40960
	ds_read_b128 v[212:215], v8 offset:40960
	ds_read_b128 v[216:219], v9 offset:40960
	ds_read_b128 v[220:223], v6 offset:45056
	ds_read_b128 v[224:227], v7 offset:45056
	ds_read_b128 v[228:231], v8 offset:45056
	ds_read_b128 v[232:235], v9 offset:45056
	s_waitcnt vmcnt(16)
	v_lshlrev_b32_e32 v16, 16, v24
	v_and_b32_e32 v17, 0xffff0000, v24
	v_lshlrev_b32_e32 v18, 16, v25
	v_and_b32_e32 v19, 0xffff0000, v25
	v_lshlrev_b32_e32 v20, 16, v26
	v_and_b32_e32 v21, 0xffff0000, v26
	v_lshlrev_b32_e32 v22, 16, v27
	v_and_b32_e32 v23, 0xffff0000, v27
	v_lshlrev_b32_e32 v24, 16, v28
	v_and_b32_e32 v25, 0xffff0000, v28
	v_lshlrev_b32_e32 v26, 16, v29
	v_and_b32_e32 v27, 0xffff0000, v29
	v_lshlrev_b32_e32 v28, 16, v30
	v_and_b32_e32 v29, 0xffff0000, v30
	v_lshlrev_b32_e32 v30, 16, v31
	v_and_b32_e32 v31, 0xffff0000, v31
	v_lshlrev_b32_e32 v80, 16, v88
	v_and_b32_e32 v81, 0xffff0000, v88
	v_lshlrev_b32_e32 v82, 16, v89
	v_and_b32_e32 v83, 0xffff0000, v89
	v_lshlrev_b32_e32 v84, 16, v90
	v_and_b32_e32 v85, 0xffff0000, v90
	v_lshlrev_b32_e32 v86, 16, v91
	v_and_b32_e32 v87, 0xffff0000, v91
	v_lshlrev_b32_e32 v88, 16, v92
	v_and_b32_e32 v89, 0xffff0000, v92
	v_lshlrev_b32_e32 v90, 16, v93
	v_and_b32_e32 v91, 0xffff0000, v93
	v_lshlrev_b32_e32 v92, 16, v94
	v_and_b32_e32 v93, 0xffff0000, v94
	v_lshlrev_b32_e32 v94, 16, v95
	v_and_b32_e32 v95, 0xffff0000, v95
	v_lshlrev_b32_e32 v32, 16, v40
	v_and_b32_e32 v33, 0xffff0000, v40
	v_lshlrev_b32_e32 v34, 16, v41
	v_and_b32_e32 v35, 0xffff0000, v41
	v_lshlrev_b32_e32 v36, 16, v42
	v_and_b32_e32 v37, 0xffff0000, v42
	v_lshlrev_b32_e32 v38, 16, v43
	v_and_b32_e32 v39, 0xffff0000, v43
	v_lshlrev_b32_e32 v40, 16, v44
	v_and_b32_e32 v41, 0xffff0000, v44
	v_lshlrev_b32_e32 v42, 16, v45
	v_and_b32_e32 v43, 0xffff0000, v45
	v_lshlrev_b32_e32 v44, 16, v46
	v_and_b32_e32 v45, 0xffff0000, v46
	v_lshlrev_b32_e32 v46, 16, v47
	v_and_b32_e32 v47, 0xffff0000, v47
	v_lshlrev_b32_e32 v96, 16, v104
	v_and_b32_e32 v97, 0xffff0000, v104
	v_lshlrev_b32_e32 v98, 16, v105
	v_and_b32_e32 v99, 0xffff0000, v105
	v_lshlrev_b32_e32 v100, 16, v106
	v_and_b32_e32 v101, 0xffff0000, v106
	v_lshlrev_b32_e32 v102, 16, v107
	v_and_b32_e32 v103, 0xffff0000, v107
	v_lshlrev_b32_e32 v104, 16, v108
	v_and_b32_e32 v105, 0xffff0000, v108
	v_lshlrev_b32_e32 v106, 16, v109
	v_and_b32_e32 v107, 0xffff0000, v109
	v_lshlrev_b32_e32 v108, 16, v110
	v_and_b32_e32 v109, 0xffff0000, v110
	v_lshlrev_b32_e32 v110, 16, v111
	v_and_b32_e32 v111, 0xffff0000, v111
	s_waitcnt lgkmcnt(0)
	v_mfma_f32_32x32x16_bf16 v[16:31], v[204:207], v[112:115], v[16:31]
	v_mfma_f32_32x32x16_bf16 v[80:95], v[128:131], v[112:115], v[80:95]
	v_mfma_f32_32x32x16_bf16 v[32:47], v[220:223], v[112:115], v[32:47]
	v_mfma_f32_32x32x16_bf16 v[96:111], v[144:147], v[112:115], v[96:111]
	v_mfma_f32_32x32x16_bf16 v[16:31], v[208:211], v[116:119], v[16:31]
	v_mfma_f32_32x32x16_bf16 v[80:95], v[132:135], v[116:119], v[80:95]
	v_mfma_f32_32x32x16_bf16 v[32:47], v[224:227], v[116:119], v[32:47]
	v_mfma_f32_32x32x16_bf16 v[96:111], v[148:151], v[116:119], v[96:111]
	v_mfma_f32_32x32x16_bf16 v[16:31], v[212:215], v[120:123], v[16:31]
	v_mfma_f32_32x32x16_bf16 v[80:95], v[136:139], v[120:123], v[80:95]
	v_mfma_f32_32x32x16_bf16 v[32:47], v[228:231], v[120:123], v[32:47]
	v_mfma_f32_32x32x16_bf16 v[96:111], v[152:155], v[120:123], v[96:111]
	v_mfma_f32_32x32x16_bf16 v[16:31], v[216:219], v[124:127], v[16:31]
	v_mfma_f32_32x32x16_bf16 v[80:95], v[140:143], v[124:127], v[80:95]
	v_mfma_f32_32x32x16_bf16 v[32:47], v[232:235], v[124:127], v[32:47]
	v_mfma_f32_32x32x16_bf16 v[96:111], v[156:159], v[124:127], v[96:111]
	s_nop 9
	v_cvt_pk_bf16_f32 v112, v80, v81
	v_cvt_pk_bf16_f32 v113, v82, v83
	v_cvt_pk_bf16_f32 v114, v84, v85
	v_cvt_pk_bf16_f32 v115, v86, v87
	v_cvt_pk_bf16_f32 v116, v88, v89
	v_cvt_pk_bf16_f32 v117, v90, v91
	v_cvt_pk_bf16_f32 v118, v92, v93
	v_cvt_pk_bf16_f32 v119, v94, v95
	v_cvt_pk_bf16_f32 v120, v96, v97
	v_cvt_pk_bf16_f32 v121, v98, v99
	v_cvt_pk_bf16_f32 v122, v100, v101
	v_cvt_pk_bf16_f32 v123, v102, v103
	v_cvt_pk_bf16_f32 v124, v104, v105
	v_cvt_pk_bf16_f32 v125, v106, v107
	v_cvt_pk_bf16_f32 v126, v108, v109
	v_cvt_pk_bf16_f32 v127, v110, v111
	global_load_dwordx4 v[88:91], v[12:13], off
	global_load_dwordx4 v[92:95], v[12:13], off offset:16
	v_lshl_add_u64 v[12:13], v[12:13], 0, s[22:23]
	global_load_dwordx4 v[104:107], v[162:163], off
	global_load_dwordx4 v[108:111], v[162:163], off offset:16
	v_lshl_add_u64 v[162:163], v[162:163], 0, s[22:23]
	ds_write_b16 v236, v112 offset:0
	ds_write_b16_d16_hi v236, v112 offset:64
	ds_write_b16 v236, v113 offset:128
	ds_write_b16_d16_hi v236, v113 offset:192
	ds_write_b16 v236, v114 offset:512
	ds_write_b16_d16_hi v236, v114 offset:576
	ds_write_b16 v236, v115 offset:640
	ds_write_b16_d16_hi v236, v115 offset:704
	ds_write_b16 v236, v116 offset:1024
	ds_write_b16_d16_hi v236, v116 offset:1088
	ds_write_b16 v236, v117 offset:1152
	ds_write_b16_d16_hi v236, v117 offset:1216
	ds_write_b16 v236, v118 offset:1536
	ds_write_b16_d16_hi v236, v118 offset:1600
	ds_write_b16 v236, v119 offset:1664
	ds_write_b16_d16_hi v236, v119 offset:1728
	s_waitcnt lgkmcnt(0)
	ds_read_b128 v[80:83], v237 offset:0
	ds_read_b128 v[84:87], v237 offset:1024
	s_waitcnt lgkmcnt(0)
	global_store_dwordx4 v[244:245], v[80:83], off
	v_lshl_add_u64 v[244:245], v[244:245], 0, s[14:15]
	global_store_dwordx4 v[244:245], v[84:87], off
	v_lshl_add_u64 v[244:245], v[244:245], 0, s[14:15]
	ds_write_b16 v236, v120 offset:0
	ds_write_b16_d16_hi v236, v120 offset:64
	ds_write_b16 v236, v121 offset:128
	ds_write_b16_d16_hi v236, v121 offset:192
	ds_write_b16 v236, v122 offset:512
	ds_write_b16_d16_hi v236, v122 offset:576
	ds_write_b16 v236, v123 offset:640
	ds_write_b16_d16_hi v236, v123 offset:704
	ds_write_b16 v236, v124 offset:1024
	ds_write_b16_d16_hi v236, v124 offset:1088
	ds_write_b16 v236, v125 offset:1152
	ds_write_b16_d16_hi v236, v125 offset:1216
	ds_write_b16 v236, v126 offset:1536
	ds_write_b16_d16_hi v236, v126 offset:1600
	ds_write_b16 v236, v127 offset:1664
	ds_write_b16_d16_hi v236, v127 offset:1728
	s_waitcnt lgkmcnt(0)
	ds_read_b128 v[96:99], v237 offset:0
	ds_read_b128 v[100:103], v237 offset:1024
	s_waitcnt lgkmcnt(0)
	global_store_dwordx4 v[244:245], v[96:99], off
	v_lshl_add_u64 v[244:245], v[244:245], 0, s[14:15]
	global_store_dwordx4 v[244:245], v[100:103], off
	v_lshl_add_u64 v[244:245], v[244:245], 0, s[14:15]
	s_add_i32 s42, s42, -1
	s_cmp_lg_u32 s42, 0
	s_cbranch_scc1 .Lscan_loop
	s_and_b64 vcc, exec, s[20:21]
	s_cbranch_vccz .LBB0_795
	v_readlane_b32 s38, v248, 10
	s_lshl_b64 s[22:23], s[40:41], 2
	v_readlane_b32 s39, v248, 11
	s_or_b64 s[22:23], s[22:23], s[38:39]
	v_lshl_add_u64 v[2:3], s[22:23], 0, v[170:171]
	v_readlane_b32 s22, v249, 24
	v_lshlrev_b64 v[2:3], 17, v[2:3]
	v_readlane_b32 s23, v249, 25
	s_lshl_b32 s86, s13, 14
	v_lshl_add_u32 v0, v200, 8, v201
	v_lshl_add_u64 v[2:3], s[22:23], 0, v[2:3]
	v_lshl_add_u64 v[2:3], v[2:3], 0, s[86:87]
	v_or_b32_e32 v0, v0, v199
	v_lshl_add_u64 v[2:3], v[0:1], 2, v[2:3]
	s_movk_i32 s13, 0x1000
	v_add_co_u32_e32 v4, vcc, s13, v2
	s_movk_i32 s13, 0x2000
	s_nop 0
	v_addc_co_u32_e32 v5, vcc, 0, v3, vcc
	v_add_co_u32_e32 v6, vcc, s13, v2
	s_movk_i32 s13, 0x3000
	s_nop 0
	v_addc_co_u32_e32 v7, vcc, 0, v3, vcc
	global_store_dword v[2:3], v16, off
	global_store_dword v[2:3], v17, off offset:256
	global_store_dword v[2:3], v18, off offset:512
	global_store_dword v[2:3], v19, off offset:768
	global_store_dword v[2:3], v20, off offset:2048
	global_store_dword v[2:3], v21, off offset:2304
	global_store_dword v[2:3], v22, off offset:2560
	global_store_dword v[2:3], v23, off offset:2816
	v_add_co_u32_e32 v2, vcc, s13, v2
	global_store_dword v[6:7], v24, off offset:-4096
	global_store_dword v[4:5], v25, off offset:256
	global_store_dword v[4:5], v26, off offset:512
	global_store_dword v[4:5], v27, off offset:768
	global_store_dword v[4:5], v28, off offset:2048
	global_store_dword v[4:5], v29, off offset:2304
	global_store_dword v[4:5], v30, off offset:2560
	global_store_dword v[4:5], v31, off offset:2816
	global_store_dword v[6:7], v32, off
	global_store_dword v[6:7], v33, off offset:256
	global_store_dword v[6:7], v34, off offset:512
	global_store_dword v[6:7], v35, off offset:768
	global_store_dword v[6:7], v36, off offset:2048
	global_store_dword v[6:7], v37, off offset:2304
	global_store_dword v[6:7], v38, off offset:2560
	global_store_dword v[6:7], v39, off offset:2816
	v_addc_co_u32_e32 v3, vcc, 0, v3, vcc
	global_store_dword v[2:3], v40, off
	global_store_dword v[2:3], v41, off offset:256
	global_store_dword v[2:3], v42, off offset:512
	global_store_dword v[2:3], v43, off offset:768
	global_store_dword v[2:3], v44, off offset:2048
	global_store_dword v[2:3], v45, off offset:2304
	global_store_dword v[2:3], v46, off offset:2560
	global_store_dword v[2:3], v47, off offset:2816
